# attention: next unit's Q fragment loads issued after this unit's last QK^T MFMA (latency under the last P.V phase and epilogue)
# baseline (speedup 1.0000x reference)
.LBB0_469:
	s_abs_i32 s0, s3
	v_cvt_f32_u32_e32 v3, s0
	s_sub_i32 s5, 0, s0
	s_add_i32 s2, s3, 0x3ff
	s_movk_i32 s4, 0xff
	v_rcp_iflag_f32_e32 v3, v3
	s_ashr_i32 s6, s2, 31
	s_abs_i32 s2, s2
	s_ashr_i32 s1, s3, 31
	v_mul_f32_e32 v3, 0x4f7ffffe, v3
	v_cvt_u32_f32_e32 v3, v3
	v_cmp_lt_u32_e32 vcc, s4, v0
	v_readfirstlane_b32 s7, v3
	s_mul_i32 s5, s5, s7
	s_mul_hi_u32 s5, s7, s5
	s_add_i32 s7, s7, s5
	s_mul_hi_u32 s7, s2, s7
	s_and_saveexec_b64 s[4:5], vcc
	s_setprio 1
	s_or_b64 exec, exec, s[4:5]
	s_mul_i32 s4, s7, s0
	s_sub_i32 s2, s2, s4
	s_xor_b32 s1, s6, s1
	s_add_i32 s4, s7, 1
	s_sub_i32 s5, s2, s0
	s_cmp_ge_u32 s2, s0
	s_cselect_b32 s4, s4, s7
	s_cselect_b32 s2, s5, s2
	s_add_i32 s5, s4, 1
	s_cmp_ge_u32 s2, s0
	s_cselect_b32 s0, s5, s4
	s_xor_b32 s0, s0, s1
	s_sub_i32 s0, s0, s1
	s_cmp_lt_i32 s0, 1
	v_lshlrev_b32_e32 v195, 4, v0
	v_and_b32_e32 v191, 3, v0
	s_cbranch_scc1 .LBB0_490
	s_cmp_lg_u32 0, -1
	s_cselect_b32 s2, 0, 0
	s_add_i32 s2, s2, 0x8000
	s_waitcnt lgkmcnt(0)
	s_add_u32 s33, s8, 0x5000000
	s_addc_u32 s34, s9, 0
	v_and_b32_e32 v253, 31, v0
	v_lshrrev_b32_e32 v3, 5, v252
	v_lshlrev_b32_e32 v5, 1, v0
	s_add_u32 s35, s8, 0x1000000
	v_lshlrev_b32_e32 v4, 3, v0
	v_and_b32_e32 v5, 32, v5
	v_and_b32_e32 v6, 0xc0, v195
	v_lshlrev_b32_e32 v7, 10, v3
	v_lshlrev_b32_e32 v8, 4, v253
	s_addc_u32 s46, s9, 0
	v_and_b32_e32 v20, 24, v4
	v_lshl_or_b32 v6, v3, 8, v6
	v_add3_u32 v228, 0, v7, v8
	v_add_u32_e32 v7, 0, v5
	s_add_u32 s47, s8, 0x7000000
	v_add3_u32 v229, v7, v20, v6
	v_lshlrev_b32_e32 v7, 9, v253
	s_addc_u32 s48, s9, 0
	v_lshl_or_b32 v22, v3, 3, v7
	v_lshlrev_b32_e32 v231, 4, v3
	v_lshlrev_b32_e32 v232, 9, v3
	v_lshrrev_b32_e32 v3, 3, v252
	s_add_u32 s49, s8, 0x7800000
	v_mov_b32_e32 v193, 0
	v_add_u32_e32 v5, s2, v5
	v_and_b32_e32 v194, 56, v4
	v_or_b32_e32 v4, 8, v3
	s_addc_u32 s50, s9, 0
	v_lshlrev_b32_e32 v192, 8, v252
	v_add3_u32 v230, v5, v20, v6
	v_lshlrev_b32_e32 v5, 6, v0
	v_lshlrev_b32_e32 v233, 7, v3
	v_lshlrev_b32_e32 v26, 10, v3
	v_lshlrev_b32_e32 v234, 7, v4
	v_lshlrev_b32_e32 v28, 10, v4
	v_or_b32_e32 v4, 16, v3
	v_or_b32_e32 v3, 24, v3
	s_add_u32 s51, s8, 0x8000000
	v_lshl_add_u64 v[34:35], s[8:9], 0, v[192:193]
	s_mov_b64 s[10:11], 0x7004000
	v_lshlrev_b32_e32 v192, 4, v191
	v_lshlrev_b32_e32 v18, 7, v252
	v_lshrrev_b32_e32 v254, 2, v252
	v_and_b32_e32 v24, 0xe00, v5
	v_lshlrev_b32_e32 v30, 10, v4
	v_lshlrev_b32_e32 v32, 10, v3
	v_xor_b32_e32 v2, 0x80000000, v2
	s_addc_u32 s52, s9, 0
	v_lshl_add_u64 v[196:197], v[34:35], 0, s[10:11]
	v_lshl_add_u64 v[34:35], s[8:9], 0, v[192:193]
	s_mov_b64 s[8:9], 0x7804000
	s_mul_i32 s1, s0, s73
	s_mov_b32 s7, 0
	v_cmp_gt_u32_e64 s[4:5], 32, v252
	v_lshlrev_b32_e32 v235, 7, v4
	v_lshlrev_b32_e32 v236, 7, v3
	v_mov_b32_e32 v3, v2
	v_mov_b32_e32 v4, v2
	v_mov_b32_e32 v5, v2
	v_mov_b32_e32 v6, v2
	v_mov_b32_e32 v7, v2
	v_mov_b32_e32 v8, v2
	v_mov_b32_e32 v9, v2
	v_mov_b32_e32 v10, v2
	v_mov_b32_e32 v11, v2
	v_mov_b32_e32 v12, v2
	v_mov_b32_e32 v13, v2
	v_mov_b32_e32 v14, v2
	v_mov_b32_e32 v15, v2
	v_mov_b32_e32 v16, v2
	v_mov_b32_e32 v17, v2
	v_lshl_add_u64 v[198:199], v[34:35], 0, s[8:9]
	v_lshlrev_b32_e32 v237, 7, v254
	s_mov_b64 s[36:37], 0
	v_lshlrev_b32_e32 v200, 1, v18
	v_lshlrev_b32_e32 v202, 1, v20
	s_mov_b64 s[8:9], 0x4000
	v_lshlrev_b32_e32 v238, 1, v22
	s_mov_b64 s[10:11], 0x8000
	s_mov_b64 s[12:13], 0xc000
	s_mov_b64 s[14:15], 0x10000
	s_mov_b64 s[16:17], 0x78000
	s_mov_b64 s[18:19], 0x70000
	s_mov_b64 s[22:23], 0x7c000
	s_mov_b64 s[24:25], 0x74000
	v_lshlrev_b32_e32 v204, 1, v24
	v_lshlrev_b32_e32 v206, 1, v26
	v_lshlrev_b32_e32 v208, 1, v28
	v_lshlrev_b32_e32 v210, 1, v30
	v_lshlrev_b32_e32 v212, 1, v32
	s_mov_b32 s101, 0
	s_mov_b32 s53, 0
	s_branch .LBB0_475

.LBB0_484:
	s_lshl_b32 s29, s29, 3
	s_sub_i32 s2, s2, s29
	s_lshl_b32 s2, s2, 8
	s_lshl_b64 s[36:37], s[36:37], 11
	s_ashr_i32 s29, s2, 31
	s_add_u32 s2, s36, s2
	s_addc_u32 s29, s37, s29
	s_lshl_b32 s30, s55, 5
	s_add_u32 s38, s2, s30
	s_addc_u32 s39, s29, 0
	s_lshl_b64 s[40:41], s[38:39], 9
	s_lshl_b64 s[36:37], s[38:39], 10
	s_add_u32 s2, s33, s36
	s_addc_u32 s30, s34, s37
	s_lshl_b32 s28, s28, 6
	s_ashr_i32 s29, s28, 31
	s_lshl_b64 s[36:37], s[28:29], 1
	s_add_u32 s28, s2, s36
	s_addc_u32 s29, s30, s37
	s_cmp_eq_u32 s101, 1
	s_cbranch_scc1 .Lqpf_have
	global_load_dwordx4 v[174:177], v238, s[28:29] nt
	global_load_dwordx4 v[170:173], v238, s[28:29] offset:32 nt
	global_load_dwordx4 v[162:165], v238, s[28:29] offset:64 nt
	global_load_dwordx4 v[154:157], v238, s[28:29] offset:96 nt
.Lqpf_have:
	s_cmp_lg_u32 0, -1
	v_mov_b64_e32 v[32:33], v[16:17]
	s_cselect_b32 s2, 0, 0
	v_mov_b64_e32 v[30:31], v[14:15]
	v_mov_b64_e32 v[28:29], v[12:13]
	v_mov_b64_e32 v[26:27], v[10:11]
	v_mov_b64_e32 v[24:25], v[8:9]
	v_mov_b64_e32 v[22:23], v[6:7]
	v_mov_b64_e32 v[20:21], v[4:5]
	v_mov_b64_e32 v[18:19], v[2:3]
	s_add_i32 s60, s2, s57
	v_lshl_add_u64 v[34:35], v[214:215], 0, s[10:11]
	s_add_i32 s2, s60, 0x4000
	s_mov_b32 s28, m0
	s_mov_b32 m0, s2
	s_nop 0
	global_load_lds_dwordx4 v[34:35], off
	s_mov_b32 m0, s28
	s_waitcnt vmcnt(3) lgkmcnt(0)
	s_barrier
	ds_read_b128 v[34:37], v228
	s_and_b32 s31, s31, 0x3ffffff0
	s_add_i32 s62, s60, 0x8000
	s_add_u32 s31, s42, s31
	s_addc_u32 s61, s43, 0
	s_add_u32 s60, s31, s44
	s_addc_u32 s61, s61, s45
	s_add_u32 s6, s42, s6
	s_addc_u32 s31, s43, 0
	s_add_u32 s42, s6, s44
	s_addc_u32 s43, s31, s45
	s_lshl_b32 s6, s56, 6
	s_and_b32 s6, s6, 0x3000
	v_lshl_add_u64 v[98:99], v[214:215], 0, s[12:13]
	v_lshl_or_b32 v192, v237, 1, s6
	v_lshl_add_u64 v[100:101], v[216:217], 0, s[8:9]
	v_mov_b32_e32 v201, 0
	s_mov_b32 s2, -1
	s_mov_b32 s30, 0
	s_movk_i32 s28, 0x4000
	s_movk_i32 s29, 0x2000
	v_mov_b32_e32 v38, v201
	v_mov_b32_e32 v39, v201
	v_lshl_add_u64 v[220:221], v[196:197], 0, s[60:61]
	s_waitcnt vmcnt(3) lgkmcnt(0)
	v_mfma_f32_32x32x16_bf16 v[66:81], v[34:37], v[174:177], v[18:33]
	ds_read_b128 v[34:37], v228 offset:512
	ds_read_b128 v[40:43], v228 offset:2560
	ds_read_b128 v[44:47], v228 offset:2048
	s_waitcnt lgkmcnt(2)
	v_mfma_f32_32x32x16_bf16 v[50:65], v[34:37], v[174:177], v[18:33]
	v_mov_b32_e32 v34, 0
	v_mov_b32_e32 v35, v201
	v_mov_b32_e32 v36, v201
	v_mov_b32_e32 v37, v201
	s_waitcnt vmcnt(2) lgkmcnt(0)
	v_mfma_f32_32x32x16_bf16 v[66:81], v[44:47], v[170:173], v[66:81]
	ds_read_b128 v[82:85], v228 offset:4608
	ds_read_b128 v[46:49], v228 offset:4096
	ds_read_b128 v[86:89], v228 offset:6656
	ds_read_b128 v[90:93], v228 offset:6144
	v_mov_b32_e32 v44, v201
	v_mov_b32_e32 v45, v201
	v_mfma_f32_32x32x16_bf16 v[50:65], v[40:43], v[170:173], v[50:65]
	v_mov_b32_e32 v40, v201
	v_mov_b32_e32 v41, v201
	v_mov_b32_e32 v42, v201
	v_mov_b32_e32 v43, v201
	s_waitcnt vmcnt(1) lgkmcnt(2)
	v_mfma_f32_32x32x16_bf16 v[66:81], v[46:49], v[162:165], v[66:81]
	v_mov_b32_e32 v46, v201
	v_mov_b32_e32 v47, v201
	v_mov_b32_e32 v48, v201
	v_mov_b32_e32 v49, v201
	v_mfma_f32_32x32x16_bf16 v[50:65], v[82:85], v[162:165], v[50:65]
	v_lshl_add_u64 v[82:83], s[42:43], 0, v[192:193]
	v_lshl_add_u64 v[222:223], v[198:199], 0, v[82:83]
	s_waitcnt vmcnt(0) lgkmcnt(0)
	v_mfma_f32_32x32x16_bf16 v[66:81], v[90:93], v[154:157], v[66:81]
	v_mfma_f32_32x32x16_bf16 v[50:65], v[86:89], v[154:157], v[50:65]
	s_nop 15
	s_nop 7
	s_waitcnt vmcnt(0) lgkmcnt(0)
	s_barrier
	s_mov_b32 s6, m0
	s_mov_b32 m0, s59
	s_nop 0
	global_load_lds_dwordx4 v[98:99], off
	s_mov_b32 m0, s6
	s_nop 0
	s_mov_b32 s6, m0
	s_mov_b32 m0, s62
	s_nop 0
	global_load_lds_dwordx4 v[100:101], off
	s_mov_b32 m0, s6
	ds_read_b128 v[98:101], v228 offset:8192
	ds_read_b128 v[186:189], v228 offset:8704
	ds_read_b128 v[182:185], v228 offset:10240
	ds_read_b128 v[178:181], v228 offset:10752
	ds_read_b128 v[142:145], v228 offset:12288
	ds_read_b128 v[138:141], v228 offset:12800
	ds_read_b128 v[134:137], v228 offset:14336
	ds_read_b128 v[130:133], v228 offset:14848
	s_nop 1
	v_exp_f32_e32 v82, v66
	v_exp_f32_e32 v83, v67
	v_exp_f32_e32 v84, v68
	v_exp_f32_e32 v85, v69
	v_exp_f32_e32 v86, v70
	v_exp_f32_e32 v87, v71
	v_exp_f32_e32 v88, v72
	v_exp_f32_e32 v89, v73
	v_exp_f32_e32 v90, v74
	v_exp_f32_e32 v91, v75
	v_exp_f32_e32 v92, v76
	v_exp_f32_e32 v93, v77
	v_exp_f32_e32 v94, v78
	v_exp_f32_e32 v95, v79
	v_exp_f32_e32 v96, v80
	v_exp_f32_e32 v97, v81
	v_exp_f32_e32 v66, v50
	v_exp_f32_e32 v67, v51
	v_exp_f32_e32 v68, v52
	v_exp_f32_e32 v69, v53
	v_exp_f32_e32 v70, v54
	v_exp_f32_e32 v71, v55
	v_exp_f32_e32 v72, v56
	v_exp_f32_e32 v73, v57
	v_exp_f32_e32 v74, v58
	v_exp_f32_e32 v75, v59
	v_exp_f32_e32 v76, v60
	v_exp_f32_e32 v77, v61
	v_exp_f32_e32 v78, v62
	v_exp_f32_e32 v79, v63
	v_exp_f32_e32 v80, v64
	v_exp_f32_e32 v81, v65
	s_waitcnt vmcnt(2) lgkmcnt(0)
	s_barrier
	v_mov_b32_e32 v50, 0
	v_mov_b32_e32 v51, v201
	v_mov_b32_e32 v52, v201
	v_mov_b32_e32 v53, v201
	v_mov_b32_e32 v54, v201
	v_mov_b32_e32 v55, v201
	v_mov_b32_e32 v56, v201
	v_mov_b32_e32 v57, v201
	v_mov_b32_e32 v58, v201
	v_mov_b32_e32 v59, v201
	v_mov_b32_e32 v60, v201
	v_mov_b32_e32 v61, v201
	v_mov_b32_e32 v62, v201
	v_mov_b32_e32 v63, v201
	v_mov_b32_e32 v64, v201
	v_mov_b32_e32 v65, v201
.LBB0_485:
	v_add_u32_e32 v192, s30, v229
	ds_read_b64_tr_b16 v[224:225], v192 offset:24576
	ds_read_b64_tr_b16 v[226:227], v192 offset:25088
	v_add_f32_e32 v102, v82, v83
	v_add_f32_e32 v102, v84, v102
	v_add_f32_e32 v102, v85, v102
	v_add_f32_e32 v102, v86, v102
	v_add_f32_e32 v102, v87, v102
	v_cvt_pk_bf16_f32 v166, v82, v83
	v_cvt_pk_bf16_f32 v167, v84, v85
	s_waitcnt lgkmcnt(9)
	v_mfma_f32_32x32x16_bf16 v[114:129], v[98:101], v[174:177], v[18:33]
	ds_read_b64_tr_b16 v[82:83], v192 offset:28672
	ds_read_b64_tr_b16 v[84:85], v192 offset:29184
	v_add_f32_e32 v98, v88, v102
	v_add_f32_e32 v98, v89, v98
	v_add_f32_e32 v98, v90, v98
	v_add_f32_e32 v146, v91, v98
	s_waitcnt lgkmcnt(10)
	v_mfma_f32_32x32x16_bf16 v[98:113], v[186:189], v[174:177], v[18:33]
	v_cvt_pk_bf16_f32 v168, v86, v87
	v_cvt_pk_bf16_f32 v169, v88, v89
	ds_read_b64_tr_b16 v[86:87], v192 offset:25600
	ds_read_b64_tr_b16 v[88:89], v192 offset:26112
	v_add_f32_e32 v146, v92, v146
	v_add_f32_e32 v146, v93, v146
	v_add_f32_e32 v146, v94, v146
	v_add_f32_e32 v146, v95, v146
	v_cvt_pk_bf16_f32 v158, v90, v91
	v_cvt_pk_bf16_f32 v159, v92, v93
	s_waitcnt lgkmcnt(11)
	v_mfma_f32_32x32x16_bf16 v[114:129], v[182:185], v[170:173], v[114:129]
	ds_read_b64_tr_b16 v[90:91], v192 offset:29696
	ds_read_b64_tr_b16 v[92:93], v192 offset:30208
	s_waitcnt lgkmcnt(12)
	v_mfma_f32_32x32x16_bf16 v[98:113], v[178:181], v[170:173], v[98:113]
	v_add_f32_e32 v146, v96, v146
	v_add_f32_e32 v146, v97, v146
	v_add_f32_e32 v146, v66, v146
	v_add_f32_e32 v146, v67, v146
	v_cvt_pk_bf16_f32 v160, v94, v95
	v_cvt_pk_bf16_f32 v161, v96, v97
	ds_read_b64_tr_b16 v[94:95], v192 offset:26624
	ds_read_b64_tr_b16 v[96:97], v192 offset:27136
	v_add_f32_e32 v146, v68, v146
	v_add_f32_e32 v146, v69, v146
	v_add_f32_e32 v146, v70, v146
	v_add_f32_e32 v146, v71, v146
	v_cvt_pk_bf16_f32 v150, v66, v67
	v_cvt_pk_bf16_f32 v151, v68, v69
	s_waitcnt lgkmcnt(13)
	v_mfma_f32_32x32x16_bf16 v[114:129], v[142:145], v[162:165], v[114:129]
	ds_read_b64_tr_b16 v[66:67], v192 offset:30720
	ds_read_b64_tr_b16 v[68:69], v192 offset:31232
	s_waitcnt lgkmcnt(14)
	v_mfma_f32_32x32x16_bf16 v[98:113], v[138:141], v[162:165], v[98:113]
	v_add_f32_e32 v142, v72, v146
	v_add_f32_e32 v142, v73, v142
	v_add_f32_e32 v142, v74, v142
	v_add_f32_e32 v142, v75, v142
	v_cvt_pk_bf16_f32 v152, v70, v71
	v_cvt_pk_bf16_f32 v153, v72, v73
	ds_read_b64_tr_b16 v[70:71], v192 offset:27648
	ds_read_b64_tr_b16 v[72:73], v192 offset:28160
	v_add_f32_e32 v138, v76, v142
	v_add_f32_e32 v138, v77, v138
	v_add_f32_e32 v138, v78, v138
	v_add_f32_e32 v138, v79, v138
	v_cvt_pk_bf16_f32 v146, v74, v75
	v_cvt_pk_bf16_f32 v147, v76, v77
	s_waitcnt lgkmcnt(14)
	v_mfma_f32_32x32x16_bf16 v[114:129], v[134:137], v[154:157], v[114:129]
	ds_read_b64_tr_b16 v[74:75], v192 offset:31744
	ds_read_b64_tr_b16 v[76:77], v192 offset:32256
	v_mfma_f32_32x32x16_bf16 v[98:113], v[130:133], v[154:157], v[98:113]
	v_add_f32_e32 v134, v80, v138
	v_add_f32_e32 v134, v81, v134
	v_add_f32_e32 v134, 0, v134
	v_cvt_pk_bf16_f32 v148, v78, v79
	v_cvt_pk_bf16_f32 v149, v80, v81
	v_lshl_add_u64 v[78:79], v[220:221], 0, s[12:13]
	s_add_i32 s6, s29, s59
	s_mov_b32 s30, m0
	s_mov_b32 m0, s6
	s_nop 0
	global_load_lds_dwordx4 v[78:79], off
	s_mov_b32 m0, s30
	v_lshl_add_u64 v[78:79], v[222:223], 0, s[8:9]
	s_add_i32 s6, s28, s58
	s_mov_b32 s30, m0
	s_mov_b32 m0, s6
	s_nop 0
	global_load_lds_dwordx4 v[78:79], off
	s_mov_b32 m0, s30
	v_add_f32_e32 v192, v201, v134
	s_waitcnt lgkmcnt(14)
	v_mfma_f32_32x32x16_bf16 v[34:49], v[166:169], v[224:227], v[34:49]
	v_exp_f32_e32 v114, v114
	v_exp_f32_e32 v115, v115
	v_exp_f32_e32 v116, v116
	v_exp_f32_e32 v117, v117
	s_waitcnt lgkmcnt(12)
	v_mfma_f32_32x32x16_bf16 v[50:65], v[166:169], v[82:85], v[50:65]
	v_exp_f32_e32 v118, v118
	v_exp_f32_e32 v119, v119
	v_exp_f32_e32 v120, v120
	v_exp_f32_e32 v121, v121
	v_add_u32_e32 v82, s28, v228
	ds_read_b128 v[78:81], v82
	ds_read_b128 v[130:133], v82 offset:512
	s_waitcnt lgkmcnt(12)
	v_mfma_f32_32x32x16_bf16 v[34:49], v[158:161], v[86:89], v[34:49]
	v_exp_f32_e32 v122, v122
	v_exp_f32_e32 v123, v123
	v_exp_f32_e32 v124, v124
	v_exp_f32_e32 v125, v125
	ds_read_b128 v[134:137], v82 offset:2048
	ds_read_b128 v[138:141], v82 offset:2560
	s_waitcnt lgkmcnt(12)
	v_mfma_f32_32x32x16_bf16 v[50:65], v[158:161], v[90:93], v[50:65]
	v_exp_f32_e32 v126, v126
	v_exp_f32_e32 v127, v127
	v_exp_f32_e32 v128, v128
	v_exp_f32_e32 v129, v129
	ds_read_b128 v[142:145], v82 offset:4096
	ds_read_b128 v[178:181], v82 offset:4608
	s_waitcnt lgkmcnt(12)
	v_mfma_f32_32x32x16_bf16 v[34:49], v[150:153], v[94:97], v[34:49]
	v_exp_f32_e32 v98, v98
	v_exp_f32_e32 v99, v99
	v_exp_f32_e32 v100, v100
	v_exp_f32_e32 v101, v101
	ds_read_b128 v[182:185], v82 offset:6144
	ds_read_b128 v[186:189], v82 offset:6656
	s_waitcnt lgkmcnt(12)
	v_mfma_f32_32x32x16_bf16 v[50:65], v[150:153], v[66:69], v[50:65]
	v_exp_f32_e32 v102, v102
	v_exp_f32_e32 v103, v103
	v_exp_f32_e32 v104, v104
	v_exp_f32_e32 v105, v105
	s_waitcnt lgkmcnt(10)
	v_mfma_f32_32x32x16_bf16 v[34:49], v[146:149], v[70:73], v[34:49]
	v_exp_f32_e32 v106, v106
	v_exp_f32_e32 v107, v107
	v_exp_f32_e32 v108, v108
	v_exp_f32_e32 v109, v109
	s_waitcnt lgkmcnt(8)
	v_mfma_f32_32x32x16_bf16 v[50:65], v[146:149], v[74:77], v[50:65]
	v_exp_f32_e32 v110, v110
	v_exp_f32_e32 v111, v111
	v_exp_f32_e32 v112, v112
	v_exp_f32_e32 v113, v113
	s_waitcnt vmcnt(2) lgkmcnt(0)
	s_barrier
	s_add_i32 s6, s28, 0x2000
	s_cmpk_lg_i32 s28, 0x4000
	s_cselect_b32 s6, s6, 0
	v_add_u32_e32 v201, s29, v229
	ds_read_b64_tr_b16 v[224:225], v201 offset:24576
	ds_read_b64_tr_b16 v[226:227], v201 offset:25088
	s_waitcnt lgkmcnt(9)
	v_mfma_f32_32x32x16_bf16 v[82:97], v[78:81], v[174:177], v[18:33]
	v_add_f32_e32 v66, v114, v115
	v_add_f32_e32 v66, v116, v66
	v_add_f32_e32 v66, v117, v66
	v_add_f32_e32 v66, v118, v66
	v_add_f32_e32 v66, v119, v66
	v_cvt_pk_bf16_f32 v166, v114, v115
	v_cvt_pk_bf16_f32 v167, v116, v117
	ds_read_b64_tr_b16 v[114:115], v201 offset:28672
	ds_read_b64_tr_b16 v[116:117], v201 offset:29184
	v_add_f32_e32 v66, v120, v66
	v_add_f32_e32 v66, v121, v66
	v_add_f32_e32 v66, v122, v66
	v_add_f32_e32 v146, v123, v66
	s_waitcnt lgkmcnt(10)
	v_mfma_f32_32x32x16_bf16 v[66:81], v[130:133], v[174:177], v[18:33]
	v_cvt_pk_bf16_f32 v168, v118, v119
	v_cvt_pk_bf16_f32 v169, v120, v121
	ds_read_b64_tr_b16 v[118:119], v201 offset:25600
	ds_read_b64_tr_b16 v[120:121], v201 offset:26112
	s_waitcnt lgkmcnt(11)
	v_mfma_f32_32x32x16_bf16 v[82:97], v[134:137], v[170:173], v[82:97]
	v_add_f32_e32 v130, v124, v146
	v_add_f32_e32 v130, v125, v130
	v_add_f32_e32 v130, v126, v130
	v_add_f32_e32 v130, v127, v130
	v_cvt_pk_bf16_f32 v158, v122, v123
	v_cvt_pk_bf16_f32 v159, v124, v125
	ds_read_b64_tr_b16 v[122:123], v201 offset:29696
	ds_read_b64_tr_b16 v[124:125], v201 offset:30208
	s_waitcnt lgkmcnt(12)
	v_mfma_f32_32x32x16_bf16 v[66:81], v[138:141], v[170:173], v[66:81]
	v_add_f32_e32 v130, v128, v130
	v_add_f32_e32 v130, v129, v130
	v_add_f32_e32 v130, v98, v130
	v_add_f32_e32 v130, v99, v130
	v_cvt_pk_bf16_f32 v160, v126, v127
	v_cvt_pk_bf16_f32 v161, v128, v129
	ds_read_b64_tr_b16 v[126:127], v201 offset:26624
	ds_read_b64_tr_b16 v[128:129], v201 offset:27136
	s_waitcnt lgkmcnt(13)
	v_mfma_f32_32x32x16_bf16 v[82:97], v[142:145], v[162:165], v[82:97]
	v_add_f32_e32 v130, v100, v130
	v_add_f32_e32 v130, v101, v130
	v_add_f32_e32 v130, v102, v130
	v_add_f32_e32 v130, v103, v130
	v_cvt_pk_bf16_f32 v150, v98, v99
	v_cvt_pk_bf16_f32 v151, v100, v101
	ds_read_b64_tr_b16 v[240:241], v201 offset:30720
	ds_read_b64_tr_b16 v[242:243], v201 offset:31232
	s_waitcnt lgkmcnt(14)
	v_mfma_f32_32x32x16_bf16 v[66:81], v[178:181], v[162:165], v[66:81]
	v_add_f32_e32 v98, v104, v130
	v_add_f32_e32 v98, v105, v98
	v_add_f32_e32 v98, v106, v98
	v_add_f32_e32 v98, v107, v98
	v_cvt_pk_bf16_f32 v152, v102, v103
	v_cvt_pk_bf16_f32 v153, v104, v105
	ds_read_b64_tr_b16 v[102:103], v201 offset:27648
	ds_read_b64_tr_b16 v[104:105], v201 offset:28160
	s_waitcnt lgkmcnt(14)
	v_mfma_f32_32x32x16_bf16 v[82:97], v[182:185], v[154:157], v[82:97]
	v_add_f32_e32 v98, v108, v98
	v_add_f32_e32 v98, v109, v98
	v_add_f32_e32 v98, v110, v98
	v_add_f32_e32 v98, v111, v98
	v_cvt_pk_bf16_f32 v146, v106, v107
	v_cvt_pk_bf16_f32 v147, v108, v109
	ds_read_b64_tr_b16 v[106:107], v201 offset:31744
	ds_read_b64_tr_b16 v[108:109], v201 offset:32256
	v_mfma_f32_32x32x16_bf16 v[66:81], v[186:189], v[154:157], v[66:81]
	v_add_f32_e32 v98, v112, v98
	v_add_f32_e32 v98, v113, v98
	v_add_f32_e32 v98, 0, v98
	v_cvt_pk_bf16_f32 v148, v110, v111
	v_cvt_pk_bf16_f32 v149, v112, v113
	s_nop 0
	v_add_f32_e32 v201, v192, v98
	v_lshl_add_u64 v[98:99], v[220:221], 0, s[14:15]
	s_add_i32 s29, s28, s59
	s_mov_b32 s30, m0
	s_mov_b32 m0, s29
	s_nop 0
	global_load_lds_dwordx4 v[98:99], off
	s_mov_b32 m0, s30
	v_lshl_add_u64 v[222:223], v[222:223], 0, s[10:11]
	s_add_i32 s29, s6, s58
	s_mov_b32 s30, m0
	s_mov_b32 m0, s29
	s_nop 0
	global_load_lds_dwordx4 v[222:223], off
	s_mov_b32 m0, s30
	s_waitcnt lgkmcnt(14)
	v_mfma_f32_32x32x16_bf16 v[34:49], v[166:169], v[224:227], v[34:49]
	v_exp_f32_e32 v82, v82
	v_exp_f32_e32 v83, v83
	v_exp_f32_e32 v84, v84
	v_exp_f32_e32 v85, v85
	s_waitcnt lgkmcnt(12)
	v_mfma_f32_32x32x16_bf16 v[50:65], v[166:169], v[114:117], v[50:65]
	v_exp_f32_e32 v86, v86
	v_exp_f32_e32 v87, v87
	v_exp_f32_e32 v88, v88
	v_exp_f32_e32 v89, v89
	v_add_u32_e32 v110, s6, v228
	ds_read_b128 v[98:101], v110
	ds_read_b128 v[186:189], v110 offset:512
	s_waitcnt lgkmcnt(12)
	v_mfma_f32_32x32x16_bf16 v[34:49], v[158:161], v[118:121], v[34:49]
	v_exp_f32_e32 v90, v90
	v_exp_f32_e32 v91, v91
	v_exp_f32_e32 v92, v92
	v_exp_f32_e32 v93, v93
	ds_read_b128 v[182:185], v110 offset:2048
	ds_read_b128 v[178:181], v110 offset:2560
	s_waitcnt lgkmcnt(12)
	v_mfma_f32_32x32x16_bf16 v[50:65], v[158:161], v[122:125], v[50:65]
	v_exp_f32_e32 v94, v94
	v_exp_f32_e32 v95, v95
	v_exp_f32_e32 v96, v96
	v_exp_f32_e32 v97, v97
	ds_read_b128 v[142:145], v110 offset:4096
	ds_read_b128 v[138:141], v110 offset:4608
	s_waitcnt lgkmcnt(12)
	v_mfma_f32_32x32x16_bf16 v[34:49], v[150:153], v[126:129], v[34:49]
	v_exp_f32_e32 v66, v66
	v_exp_f32_e32 v67, v67
	v_exp_f32_e32 v68, v68
	v_exp_f32_e32 v69, v69
	ds_read_b128 v[134:137], v110 offset:6144
	ds_read_b128 v[130:133], v110 offset:6656
	s_waitcnt lgkmcnt(12)
	v_mfma_f32_32x32x16_bf16 v[50:65], v[150:153], v[240:243], v[50:65]
	v_exp_f32_e32 v70, v70
	v_exp_f32_e32 v71, v71
	v_exp_f32_e32 v72, v72
	v_exp_f32_e32 v73, v73
	s_waitcnt lgkmcnt(10)
	v_mfma_f32_32x32x16_bf16 v[34:49], v[146:149], v[102:105], v[34:49]
	v_exp_f32_e32 v74, v74
	v_exp_f32_e32 v75, v75
	v_exp_f32_e32 v76, v76
	v_exp_f32_e32 v77, v77
	s_waitcnt lgkmcnt(8)
	v_mfma_f32_32x32x16_bf16 v[50:65], v[146:149], v[106:109], v[50:65]
	v_exp_f32_e32 v78, v78
	v_exp_f32_e32 v79, v79
	v_exp_f32_e32 v80, v80
	v_exp_f32_e32 v81, v81
	s_add_i32 s31, s6, 0x2000
	s_waitcnt vmcnt(2) lgkmcnt(0)
	s_barrier
	s_cmpk_lg_i32 s6, 0x4000
	s_mov_b32 s30, s28
	s_cselect_b32 s28, s31, 0
	s_add_i32 s2, s2, 2
	v_lshl_add_u64 v[220:221], v[220:221], 0, s[10:11]
	s_mov_b32 s29, s6
	s_cmp_gt_u32 s2, 24
	s_cbranch_scc0 .LBB0_485
	ds_read_b64_tr_b16 v[220:221], v229 offset:40960
	ds_read_b64_tr_b16 v[222:223], v229 offset:41472
	v_add_f32_e32 v102, v82, v83
	v_add_f32_e32 v102, v84, v102
	v_add_f32_e32 v102, v85, v102
	v_add_f32_e32 v102, v86, v102
	v_add_f32_e32 v102, v87, v102
	v_cvt_pk_bf16_f32 v166, v82, v83
	v_cvt_pk_bf16_f32 v167, v84, v85
	s_waitcnt lgkmcnt(9)
	v_mfma_f32_32x32x16_bf16 v[114:129], v[98:101], v[174:177], v[18:33]
	ds_read_b64_tr_b16 v[82:83], v229 offset:45056
	ds_read_b64_tr_b16 v[84:85], v229 offset:45568
	v_add_f32_e32 v98, v88, v102
	v_add_f32_e32 v98, v89, v98
	v_add_f32_e32 v98, v90, v98
	v_add_f32_e32 v146, v91, v98
	s_waitcnt lgkmcnt(10)
	v_mfma_f32_32x32x16_bf16 v[98:113], v[186:189], v[174:177], v[18:33]
	v_cvt_pk_bf16_f32 v168, v86, v87
	v_cvt_pk_bf16_f32 v169, v88, v89
	ds_read_b64_tr_b16 v[86:87], v229 offset:41984
	ds_read_b64_tr_b16 v[88:89], v229 offset:42496
	v_add_f32_e32 v146, v92, v146
	v_add_f32_e32 v146, v93, v146
	v_add_f32_e32 v146, v94, v146
	v_add_f32_e32 v146, v95, v146
	v_cvt_pk_bf16_f32 v158, v90, v91
	v_cvt_pk_bf16_f32 v159, v92, v93
	s_waitcnt lgkmcnt(11)
	v_mfma_f32_32x32x16_bf16 v[114:129], v[182:185], v[170:173], v[114:129]
	ds_read_b64_tr_b16 v[90:91], v229 offset:46080
	ds_read_b64_tr_b16 v[92:93], v229 offset:46592
	s_waitcnt lgkmcnt(12)
	v_mfma_f32_32x32x16_bf16 v[98:113], v[178:181], v[170:173], v[98:113]
	v_add_f32_e32 v146, v96, v146
	v_add_f32_e32 v146, v97, v146
	v_add_f32_e32 v146, v66, v146
	v_add_f32_e32 v146, v67, v146
	v_cvt_pk_bf16_f32 v160, v94, v95
	v_cvt_pk_bf16_f32 v161, v96, v97
	ds_read_b64_tr_b16 v[94:95], v229 offset:43008
	ds_read_b64_tr_b16 v[96:97], v229 offset:43520
	v_add_f32_e32 v146, v68, v146
	v_add_f32_e32 v146, v69, v146
	v_add_f32_e32 v146, v70, v146
	v_add_f32_e32 v146, v71, v146
	v_cvt_pk_bf16_f32 v150, v66, v67
	v_cvt_pk_bf16_f32 v151, v68, v69
	s_waitcnt lgkmcnt(13)
	v_mfma_f32_32x32x16_bf16 v[114:129], v[142:145], v[162:165], v[114:129]
	ds_read_b64_tr_b16 v[66:67], v229 offset:47104
	ds_read_b64_tr_b16 v[68:69], v229 offset:47616
	s_waitcnt lgkmcnt(14)
	v_mfma_f32_32x32x16_bf16 v[98:113], v[138:141], v[162:165], v[98:113]
	v_add_f32_e32 v142, v72, v146
	v_add_f32_e32 v142, v73, v142
	v_add_f32_e32 v142, v74, v142
	v_add_f32_e32 v142, v75, v142
	v_cvt_pk_bf16_f32 v152, v70, v71
	v_cvt_pk_bf16_f32 v153, v72, v73
	ds_read_b64_tr_b16 v[70:71], v229 offset:44032
	ds_read_b64_tr_b16 v[72:73], v229 offset:44544
	v_add_f32_e32 v138, v76, v142
	v_add_f32_e32 v138, v77, v138
	v_add_f32_e32 v138, v78, v138
	v_add_f32_e32 v138, v79, v138
	v_cvt_pk_bf16_f32 v146, v74, v75
	v_cvt_pk_bf16_f32 v147, v76, v77
	s_waitcnt lgkmcnt(14)
	v_mfma_f32_32x32x16_bf16 v[114:129], v[134:137], v[154:157], v[114:129]
	ds_read_b64_tr_b16 v[74:75], v229 offset:48128
	ds_read_b64_tr_b16 v[76:77], v229 offset:48640
	v_mfma_f32_32x32x16_bf16 v[98:113], v[130:133], v[154:157], v[98:113]
	v_add_f32_e32 v134, v80, v138
	v_add_f32_e32 v134, v81, v134
	v_add_f32_e32 v178, 0, v134
	v_cvt_pk_bf16_f32 v148, v78, v79
	v_cvt_pk_bf16_f32 v149, v80, v81
	s_cmp_lg_u32 0, -1
	s_cselect_b32 s6, 0, 0
	v_lshl_add_u64 v[78:79], v[214:215], 0, s[16:17]
	s_mov_b32 s2, m0
	s_mov_b32 m0, s59
	s_nop 0
	global_load_lds_dwordx4 v[78:79], off
	s_mov_b32 m0, s2
	s_add_i32 s6, s6, s57
	v_lshl_add_u64 v[78:79], v[216:217], 0, s[18:19]
	s_add_i32 s2, s6, 0x8000
	s_mov_b32 s28, m0
	s_mov_b32 m0, s2
	s_nop 0
	global_load_lds_dwordx4 v[78:79], off
	s_mov_b32 m0, s28
	s_waitcnt lgkmcnt(14)
	v_mfma_f32_32x32x16_bf16 v[34:49], v[166:169], v[220:223], v[34:49]
	v_exp_f32_e32 v114, v114
	v_exp_f32_e32 v115, v115
	v_exp_f32_e32 v116, v116
	v_exp_f32_e32 v117, v117
	s_waitcnt lgkmcnt(12)
	v_mfma_f32_32x32x16_bf16 v[50:65], v[166:169], v[82:85], v[50:65]
	v_exp_f32_e32 v118, v118
	v_exp_f32_e32 v119, v119
	v_exp_f32_e32 v120, v120
	v_exp_f32_e32 v121, v121
	ds_read_b128 v[78:81], v228 offset:8192
	ds_read_b128 v[130:133], v228 offset:8704
	s_waitcnt lgkmcnt(12)
	v_mfma_f32_32x32x16_bf16 v[34:49], v[158:161], v[86:89], v[34:49]
	v_exp_f32_e32 v122, v122
	v_exp_f32_e32 v123, v123
	v_exp_f32_e32 v124, v124
	v_exp_f32_e32 v125, v125
	ds_read_b128 v[134:137], v228 offset:10240
	ds_read_b128 v[138:141], v228 offset:10752
	s_waitcnt lgkmcnt(12)
	v_mfma_f32_32x32x16_bf16 v[50:65], v[158:161], v[90:93], v[50:65]
	v_exp_f32_e32 v126, v126
	v_exp_f32_e32 v127, v127
	v_exp_f32_e32 v128, v128
	v_exp_f32_e32 v129, v129
	ds_read_b128 v[142:145], v228 offset:12288
	ds_read_b128 v[180:183], v228 offset:12800
	s_waitcnt lgkmcnt(12)
	v_mfma_f32_32x32x16_bf16 v[34:49], v[150:153], v[94:97], v[34:49]
	v_exp_f32_e32 v98, v98
	v_exp_f32_e32 v99, v99
	v_exp_f32_e32 v100, v100
	v_exp_f32_e32 v101, v101
	ds_read_b128 v[184:187], v228 offset:14336
	ds_read_b128 v[220:223], v228 offset:14848
	s_waitcnt lgkmcnt(12)
	v_mfma_f32_32x32x16_bf16 v[50:65], v[150:153], v[66:69], v[50:65]
	v_exp_f32_e32 v102, v102
	v_exp_f32_e32 v103, v103
	v_exp_f32_e32 v104, v104
	v_exp_f32_e32 v105, v105
	s_waitcnt lgkmcnt(10)
	v_mfma_f32_32x32x16_bf16 v[34:49], v[146:149], v[70:73], v[34:49]
	v_exp_f32_e32 v106, v106
	v_exp_f32_e32 v107, v107
	v_exp_f32_e32 v108, v108
	v_exp_f32_e32 v109, v109
	s_waitcnt lgkmcnt(8)
	v_mfma_f32_32x32x16_bf16 v[50:65], v[146:149], v[74:77], v[50:65]
	v_exp_f32_e32 v110, v110
	v_exp_f32_e32 v111, v111
	v_exp_f32_e32 v112, v112
	v_exp_f32_e32 v113, v113
	s_waitcnt vmcnt(2) lgkmcnt(0)
	s_barrier
	ds_read_b64_tr_b16 v[240:241], v229 offset:24576
	ds_read_b64_tr_b16 v[242:243], v229 offset:25088
	v_add_f32_e32 v66, v114, v115
	v_add_f32_e32 v66, v116, v66
	v_add_f32_e32 v66, v117, v66
	v_add_f32_e32 v66, v118, v66
	v_add_f32_e32 v66, v119, v66
	v_cvt_pk_bf16_f32 v166, v114, v115
	v_cvt_pk_bf16_f32 v167, v116, v117
	s_waitcnt lgkmcnt(9)
	v_mfma_f32_32x32x16_bf16 v[82:97], v[78:81], v[174:177], v[18:33]
	ds_read_b64_tr_b16 v[114:115], v229 offset:28672
	ds_read_b64_tr_b16 v[116:117], v229 offset:29184
	v_add_f32_e32 v66, v120, v66
	v_add_f32_e32 v66, v121, v66
	v_add_f32_e32 v66, v122, v66
	v_add_f32_e32 v146, v123, v66
	s_waitcnt lgkmcnt(10)
	v_mfma_f32_32x32x16_bf16 v[66:81], v[130:133], v[174:177], v[18:33]
	v_cvt_pk_bf16_f32 v168, v118, v119
	v_cvt_pk_bf16_f32 v169, v120, v121
	ds_read_b64_tr_b16 v[118:119], v229 offset:25600
	ds_read_b64_tr_b16 v[120:121], v229 offset:26112
	v_add_f32_e32 v130, v124, v146
	v_add_f32_e32 v130, v125, v130
	v_add_f32_e32 v130, v126, v130
	v_add_f32_e32 v130, v127, v130
	v_cvt_pk_bf16_f32 v158, v122, v123
	v_cvt_pk_bf16_f32 v159, v124, v125
	s_waitcnt lgkmcnt(11)
	v_mfma_f32_32x32x16_bf16 v[82:97], v[134:137], v[170:173], v[82:97]
	ds_read_b64_tr_b16 v[122:123], v229 offset:29696
	ds_read_b64_tr_b16 v[124:125], v229 offset:30208
	s_waitcnt lgkmcnt(12)
	v_mfma_f32_32x32x16_bf16 v[66:81], v[138:141], v[170:173], v[66:81]
	v_add_f32_e32 v130, v128, v130
	v_add_f32_e32 v130, v129, v130
	v_add_f32_e32 v130, v98, v130
	v_add_f32_e32 v130, v99, v130
	v_cvt_pk_bf16_f32 v160, v126, v127
	v_cvt_pk_bf16_f32 v161, v128, v129
	ds_read_b64_tr_b16 v[126:127], v229 offset:26624
	ds_read_b64_tr_b16 v[128:129], v229 offset:27136
	v_add_f32_e32 v130, v100, v130
	v_add_f32_e32 v130, v101, v130
	v_add_f32_e32 v130, v102, v130
	v_add_f32_e32 v130, v103, v130
	v_cvt_pk_bf16_f32 v150, v98, v99
	v_cvt_pk_bf16_f32 v151, v100, v101
	s_waitcnt lgkmcnt(13)
	v_mfma_f32_32x32x16_bf16 v[82:97], v[142:145], v[162:165], v[82:97]
	ds_read_b64_tr_b16 v[98:99], v229 offset:30720
	ds_read_b64_tr_b16 v[100:101], v229 offset:31232
	s_waitcnt lgkmcnt(14)
	v_mfma_f32_32x32x16_bf16 v[66:81], v[180:183], v[162:165], v[66:81]
	v_add_f32_e32 v130, v104, v130
	v_add_f32_e32 v130, v105, v130
	v_add_f32_e32 v130, v106, v130
	v_add_f32_e32 v130, v107, v130
	v_cvt_pk_bf16_f32 v152, v102, v103
	v_cvt_pk_bf16_f32 v153, v104, v105
	ds_read_b64_tr_b16 v[102:103], v229 offset:27648
	ds_read_b64_tr_b16 v[104:105], v229 offset:28160
	v_add_f32_e32 v130, v108, v130
	v_add_f32_e32 v130, v109, v130
	v_add_f32_e32 v130, v110, v130
	v_add_f32_e32 v130, v111, v130
	v_cvt_pk_bf16_f32 v146, v106, v107
	v_cvt_pk_bf16_f32 v147, v108, v109
	s_waitcnt lgkmcnt(14)
	v_mfma_f32_32x32x16_bf16 v[82:97], v[184:187], v[154:157], v[82:97]
	ds_read_b64_tr_b16 v[106:107], v229 offset:31744
	ds_read_b64_tr_b16 v[108:109], v229 offset:32256
	v_mfma_f32_32x32x16_bf16 v[66:81], v[220:223], v[154:157], v[66:81]
	v_add_f32_e32 v130, v112, v130
	v_add_f32_e32 v130, v113, v130
	v_add_f32_e32 v179, 0, v130
	v_cvt_pk_bf16_f32 v148, v110, v111
	v_cvt_pk_bf16_f32 v149, v112, v113
	v_lshl_add_u64 v[110:111], v[214:215], 0, s[22:23]
	s_add_i32 s28, s6, 0x2000
	s_mov_b32 s29, m0
	s_mov_b32 m0, s28
	s_nop 0
	global_load_lds_dwordx4 v[110:111], off
	s_mov_b32 m0, s29
	v_lshl_add_u64 v[110:111], v[216:217], 0, s[24:25]
	s_add_i32 s6, s6, 0xa000
	s_mov_b32 s28, m0
	s_mov_b32 m0, s6
	s_nop 0
	global_load_lds_dwordx4 v[110:111], off
	s_mov_b32 m0, s28
	s_waitcnt lgkmcnt(14)
	v_mfma_f32_32x32x16_bf16 v[34:49], v[166:169], v[240:243], v[34:49]
	v_exp_f32_e32 v82, v82
	v_exp_f32_e32 v83, v83
	v_exp_f32_e32 v84, v84
	v_exp_f32_e32 v85, v85
	s_waitcnt lgkmcnt(12)
	v_mfma_f32_32x32x16_bf16 v[50:65], v[166:169], v[114:117], v[50:65]
	v_exp_f32_e32 v86, v86
	v_exp_f32_e32 v87, v87
	v_exp_f32_e32 v88, v88
	v_exp_f32_e32 v89, v89
	ds_read_b128 v[110:113], v228 offset:16384
	ds_read_b128 v[114:117], v228 offset:16896
	s_waitcnt lgkmcnt(12)
	v_mfma_f32_32x32x16_bf16 v[34:49], v[158:161], v[118:121], v[34:49]
	v_exp_f32_e32 v90, v90
	v_exp_f32_e32 v91, v91
	v_exp_f32_e32 v92, v92
	v_exp_f32_e32 v93, v93
	ds_read_b128 v[118:121], v228 offset:18432
	ds_read_b128 v[180:183], v228 offset:18944
	s_waitcnt lgkmcnt(12)
	v_mfma_f32_32x32x16_bf16 v[50:65], v[158:161], v[122:125], v[50:65]
	v_exp_f32_e32 v94, v94
	v_exp_f32_e32 v95, v95
	v_exp_f32_e32 v96, v96
	v_exp_f32_e32 v97, v97
	ds_read_b128 v[122:125], v228 offset:20480
	ds_read_b128 v[184:187], v228 offset:20992
	s_waitcnt lgkmcnt(12)
	v_mfma_f32_32x32x16_bf16 v[34:49], v[150:153], v[126:129], v[34:49]
	v_exp_f32_e32 v66, v66
	v_exp_f32_e32 v67, v67
	v_exp_f32_e32 v68, v68
	v_exp_f32_e32 v69, v69
	ds_read_b128 v[126:129], v228 offset:22528
	ds_read_b128 v[220:223], v228 offset:23040
	s_waitcnt lgkmcnt(12)
	v_mfma_f32_32x32x16_bf16 v[50:65], v[150:153], v[98:101], v[50:65]
	v_exp_f32_e32 v70, v70
	v_exp_f32_e32 v71, v71
	v_exp_f32_e32 v72, v72
	v_exp_f32_e32 v73, v73
	s_waitcnt lgkmcnt(10)
	v_mfma_f32_32x32x16_bf16 v[34:49], v[146:149], v[102:105], v[34:49]
	v_exp_f32_e32 v74, v74
	v_exp_f32_e32 v75, v75
	v_exp_f32_e32 v76, v76
	v_exp_f32_e32 v77, v77
	s_waitcnt lgkmcnt(8)
	v_mfma_f32_32x32x16_bf16 v[50:65], v[146:149], v[106:109], v[50:65]
	v_exp_f32_e32 v78, v78
	v_exp_f32_e32 v79, v79
	v_exp_f32_e32 v80, v80
	v_exp_f32_e32 v81, v81
	s_waitcnt vmcnt(2) lgkmcnt(0)
	s_barrier
	ds_read_b64_tr_b16 v[240:241], v229 offset:32768
	ds_read_b64_tr_b16 v[242:243], v229 offset:33280
	v_add_f32_e32 v98, v82, v83
	v_add_f32_e32 v98, v84, v98
	v_add_f32_e32 v98, v85, v98
	v_add_f32_e32 v98, v86, v98
	v_add_f32_e32 v98, v87, v98
	v_cvt_pk_bf16_f32 v166, v82, v83
	v_cvt_pk_bf16_f32 v167, v84, v85
	s_waitcnt lgkmcnt(9)
	v_mfma_f32_32x32x16_bf16 v[130:145], v[110:113], v[174:177], v[18:33]
	ds_read_b64_tr_b16 v[82:83], v229 offset:36864
	ds_read_b64_tr_b16 v[84:85], v229 offset:37376
	v_add_f32_e32 v98, v88, v98
	v_add_f32_e32 v98, v89, v98
	v_add_f32_e32 v98, v90, v98
	v_add_f32_e32 v146, v91, v98
	s_waitcnt lgkmcnt(10)
	v_mfma_f32_32x32x16_bf16 v[98:113], v[114:117], v[174:177], v[18:33]
	v_cvt_pk_bf16_f32 v168, v86, v87
	v_cvt_pk_bf16_f32 v169, v88, v89
	ds_read_b64_tr_b16 v[86:87], v229 offset:33792
	ds_read_b64_tr_b16 v[88:89], v229 offset:34304
	v_add_f32_e32 v114, v92, v146
	v_add_f32_e32 v114, v93, v114
	v_add_f32_e32 v114, v94, v114
	v_add_f32_e32 v114, v95, v114
	v_cvt_pk_bf16_f32 v158, v90, v91
	v_cvt_pk_bf16_f32 v159, v92, v93
	s_waitcnt lgkmcnt(11)
	v_mfma_f32_32x32x16_bf16 v[130:145], v[118:121], v[170:173], v[130:145]
	ds_read_b64_tr_b16 v[90:91], v229 offset:37888
	ds_read_b64_tr_b16 v[92:93], v229 offset:38400
	s_waitcnt lgkmcnt(12)
	v_mfma_f32_32x32x16_bf16 v[98:113], v[180:183], v[170:173], v[98:113]
	v_add_f32_e32 v114, v96, v114
	v_add_f32_e32 v114, v97, v114
	v_add_f32_e32 v114, v66, v114
	v_add_f32_e32 v114, v67, v114
	v_cvt_pk_bf16_f32 v160, v94, v95
	v_cvt_pk_bf16_f32 v161, v96, v97
	ds_read_b64_tr_b16 v[94:95], v229 offset:34816
	ds_read_b64_tr_b16 v[96:97], v229 offset:35328
	v_add_f32_e32 v114, v68, v114
	v_add_f32_e32 v114, v69, v114
	v_add_f32_e32 v114, v70, v114
	v_add_f32_e32 v114, v71, v114
	v_cvt_pk_bf16_f32 v150, v66, v67
	v_cvt_pk_bf16_f32 v151, v68, v69
	s_waitcnt lgkmcnt(13)
	v_mfma_f32_32x32x16_bf16 v[130:145], v[122:125], v[162:165], v[130:145]
	ds_read_b64_tr_b16 v[66:67], v229 offset:38912
	ds_read_b64_tr_b16 v[68:69], v229 offset:39424
	s_waitcnt lgkmcnt(14)
	v_mfma_f32_32x32x16_bf16 v[98:113], v[184:187], v[162:165], v[98:113]
	v_add_f32_e32 v114, v72, v114
	v_add_f32_e32 v114, v73, v114
	v_add_f32_e32 v114, v74, v114
	v_add_f32_e32 v114, v75, v114
	v_cvt_pk_bf16_f32 v152, v70, v71
	v_cvt_pk_bf16_f32 v153, v72, v73
	ds_read_b64_tr_b16 v[70:71], v229 offset:35840
	ds_read_b64_tr_b16 v[72:73], v229 offset:36352
	v_add_f32_e32 v114, v76, v114
	v_add_f32_e32 v114, v77, v114
	v_add_f32_e32 v114, v78, v114
	v_add_f32_e32 v114, v79, v114
	v_cvt_pk_bf16_f32 v146, v74, v75
	v_cvt_pk_bf16_f32 v147, v76, v77
	s_waitcnt lgkmcnt(14)
	v_mfma_f32_32x32x16_bf16 v[130:145], v[126:129], v[154:157], v[130:145]
	ds_read_b64_tr_b16 v[74:75], v229 offset:39936
	ds_read_b64_tr_b16 v[76:77], v229 offset:40448
	v_mfma_f32_32x32x16_bf16 v[98:113], v[220:223], v[154:157], v[98:113]
	v_add_f32_e32 v114, v80, v114
	v_add_f32_e32 v114, v81, v114
	v_add_f32_e32 v180, 0, v114
	v_cvt_pk_bf16_f32 v148, v78, v79
	v_cvt_pk_bf16_f32 v149, v80, v81
	v_lshl_add_u64 v[78:79], v[216:217], 0, s[16:17]
	s_mov_b32 s6, m0
	s_mov_b32 m0, s58
	s_nop 0
	global_load_lds_dwordx4 v[78:79], off
	s_mov_b32 m0, s6
	s_waitcnt lgkmcnt(14)
	v_mfma_f32_32x32x16_bf16 v[34:49], v[166:169], v[240:243], v[34:49]
	s_nop 0
	v_exp_f32_e32 v130, v130
	v_exp_f32_e32 v131, v131
	v_exp_f32_e32 v132, v132
	v_exp_f32_e32 v133, v133
	s_waitcnt lgkmcnt(12)
	v_mfma_f32_32x32x16_bf16 v[50:65], v[166:169], v[82:85], v[50:65]
	v_exp_f32_e32 v134, v134
	v_exp_f32_e32 v135, v135
	v_exp_f32_e32 v136, v136
	v_exp_f32_e32 v137, v137
	ds_read_b128 v[78:81], v228
	ds_read_b128 v[182:185], v228 offset:512
	s_waitcnt lgkmcnt(12)
	v_mfma_f32_32x32x16_bf16 v[34:49], v[158:161], v[86:89], v[34:49]
	v_exp_f32_e32 v138, v138
	v_exp_f32_e32 v139, v139
	v_exp_f32_e32 v140, v140
	v_exp_f32_e32 v141, v141
	ds_read_b128 v[186:189], v228 offset:2048
	ds_read_b128 v[220:223], v228 offset:2560
	s_waitcnt lgkmcnt(12)
	v_mfma_f32_32x32x16_bf16 v[50:65], v[158:161], v[90:93], v[50:65]
	v_exp_f32_e32 v142, v142
	v_exp_f32_e32 v143, v143
	v_exp_f32_e32 v144, v144
	v_exp_f32_e32 v145, v145
	ds_read_b128 v[240:243], v228 offset:4096
	ds_read_b128 v[244:247], v228 offset:4608
	s_waitcnt lgkmcnt(12)
	v_mfma_f32_32x32x16_bf16 v[34:49], v[150:153], v[94:97], v[34:49]
	v_exp_f32_e32 v98, v98
	v_exp_f32_e32 v99, v99
	v_exp_f32_e32 v100, v100
	v_exp_f32_e32 v101, v101
	ds_read_b128 v[248:251], v228 offset:6144
	ds_read_b128 v[224:227], v228 offset:6656
	s_waitcnt lgkmcnt(12)
	v_mfma_f32_32x32x16_bf16 v[50:65], v[150:153], v[66:69], v[50:65]
	v_exp_f32_e32 v102, v102
	v_exp_f32_e32 v103, v103
	v_exp_f32_e32 v104, v104
	v_exp_f32_e32 v105, v105
	s_waitcnt lgkmcnt(10)
	v_mfma_f32_32x32x16_bf16 v[34:49], v[146:149], v[70:73], v[34:49]
	v_exp_f32_e32 v106, v106
	v_exp_f32_e32 v107, v107
	v_exp_f32_e32 v108, v108
	v_exp_f32_e32 v109, v109
	s_waitcnt lgkmcnt(8)
	v_mfma_f32_32x32x16_bf16 v[50:65], v[146:149], v[74:77], v[50:65]
	v_exp_f32_e32 v110, v110
	v_exp_f32_e32 v111, v111
	v_exp_f32_e32 v112, v112
	v_exp_f32_e32 v113, v113
	s_waitcnt vmcnt(1) lgkmcnt(0)
	s_barrier
	ds_read_b64_tr_b16 v[66:67], v229 offset:40960
	ds_read_b64_tr_b16 v[68:69], v229 offset:41472
	v_add_f32_e32 v70, v130, v131
	v_add_f32_e32 v70, v132, v70
	v_add_f32_e32 v70, v133, v70
	v_add_f32_e32 v70, v134, v70
	v_add_f32_e32 v74, v135, v70
	v_cvt_pk_bf16_f32 v166, v130, v131
	v_cvt_pk_bf16_f32 v167, v132, v133
	s_waitcnt lgkmcnt(9)
	v_mfma_f32_32x32x16_bf16 v[114:129], v[78:81], v[174:177], v[18:33]
	ds_read_b64_tr_b16 v[70:71], v229 offset:45056
	ds_read_b64_tr_b16 v[72:73], v229 offset:45568
	v_add_f32_e32 v74, v136, v74
	v_add_f32_e32 v74, v137, v74
	v_add_f32_e32 v74, v138, v74
	v_add_f32_e32 v78, v139, v74
	v_cvt_pk_bf16_f32 v168, v134, v135
	v_cvt_pk_bf16_f32 v169, v136, v137
	s_waitcnt lgkmcnt(10)
	v_mfma_f32_32x32x16_bf16 v[82:97], v[182:185], v[174:177], v[18:33]
	ds_read_b64_tr_b16 v[74:75], v229 offset:41984
	ds_read_b64_tr_b16 v[76:77], v229 offset:42496
	v_add_f32_e32 v78, v140, v78
	v_add_f32_e32 v78, v141, v78
	v_add_f32_e32 v78, v142, v78
	v_add_f32_e32 v130, v143, v78
	v_cvt_pk_bf16_f32 v158, v138, v139
	v_cvt_pk_bf16_f32 v159, v140, v141
	s_waitcnt lgkmcnt(11)
	v_mfma_f32_32x32x16_bf16 v[114:129], v[186:189], v[170:173], v[114:129]
	ds_read_b64_tr_b16 v[78:79], v229 offset:46080
	ds_read_b64_tr_b16 v[80:81], v229 offset:46592
	v_add_f32_e32 v130, v144, v130
	v_add_f32_e32 v130, v145, v130
	v_add_f32_e32 v130, v98, v130
	v_add_f32_e32 v134, v99, v130
	v_cvt_pk_bf16_f32 v160, v142, v143
	v_cvt_pk_bf16_f32 v161, v144, v145
	s_waitcnt lgkmcnt(12)
	v_mfma_f32_32x32x16_bf16 v[82:97], v[220:223], v[170:173], v[82:97]
	ds_read_b64_tr_b16 v[130:131], v229 offset:43008
	ds_read_b64_tr_b16 v[132:133], v229 offset:43520
	v_add_f32_e32 v134, v100, v134
	v_add_f32_e32 v134, v101, v134
	v_add_f32_e32 v134, v102, v134
	v_add_f32_e32 v138, v103, v134
	v_cvt_pk_bf16_f32 v150, v98, v99
	v_cvt_pk_bf16_f32 v151, v100, v101
	s_waitcnt lgkmcnt(13)
	v_mfma_f32_32x32x16_bf16 v[114:129], v[240:243], v[162:165], v[114:129]
	ds_read_b64_tr_b16 v[134:135], v229 offset:47104
	ds_read_b64_tr_b16 v[136:137], v229 offset:47616
	v_add_f32_e32 v98, v104, v138
	v_add_f32_e32 v98, v105, v98
	v_add_f32_e32 v98, v106, v98
	v_add_f32_e32 v98, v107, v98
	v_cvt_pk_bf16_f32 v152, v102, v103
	v_cvt_pk_bf16_f32 v153, v104, v105
	s_waitcnt lgkmcnt(14)
	v_mfma_f32_32x32x16_bf16 v[82:97], v[244:247], v[162:165], v[82:97]
	ds_read_b64_tr_b16 v[100:101], v229 offset:44032
	ds_read_b64_tr_b16 v[102:103], v229 offset:44544
	v_add_f32_e32 v98, v108, v98
	v_add_f32_e32 v98, v109, v98
	v_add_f32_e32 v98, v110, v98
	v_add_f32_e32 v98, v111, v98
	v_cvt_pk_bf16_f32 v146, v106, v107
	v_cvt_pk_bf16_f32 v147, v108, v109
	s_waitcnt lgkmcnt(14)
	v_mfma_f32_32x32x16_bf16 v[114:129], v[248:251], v[154:157], v[114:129]
	ds_read_b64_tr_b16 v[104:105], v229 offset:48128
	ds_read_b64_tr_b16 v[106:107], v229 offset:48640
	v_add_f32_e32 v98, v112, v98
	v_add_f32_e32 v98, v113, v98
	v_add_f32_e32 v98, 0, v98
	v_cvt_pk_bf16_f32 v148, v110, v111
	v_cvt_pk_bf16_f32 v149, v112, v113
	v_mfma_f32_32x32x16_bf16 v[82:97], v[224:227], v[154:157], v[82:97]
	v_lshl_add_u64 v[108:109], v[216:217], 0, s[22:23]
	s_mov_b32 s6, m0
	s_mov_b32 m0, s2
	s_nop 0
	global_load_lds_dwordx4 v[108:109], off
	s_mov_b32 m0, s6
	s_waitcnt lgkmcnt(14)
	v_mfma_f32_32x32x16_bf16 v[34:49], v[166:169], v[66:69], v[34:49]
	s_nop 0
	v_exp_f32_e32 v114, v114
	v_exp_f32_e32 v115, v115
	v_exp_f32_e32 v116, v116
	v_exp_f32_e32 v117, v117
	s_waitcnt lgkmcnt(12)
	v_mfma_f32_32x32x16_bf16 v[50:65], v[166:169], v[70:73], v[50:65]
	v_exp_f32_e32 v118, v118
	v_exp_f32_e32 v119, v119
	v_exp_f32_e32 v120, v120
	v_exp_f32_e32 v121, v121
	ds_read_b128 v[108:111], v228 offset:8192
	ds_read_b128 v[138:141], v228 offset:8704
	s_waitcnt lgkmcnt(12)
	v_mfma_f32_32x32x16_bf16 v[34:49], v[158:161], v[74:77], v[34:49]
	v_exp_f32_e32 v122, v122
	v_exp_f32_e32 v123, v123
	v_exp_f32_e32 v124, v124
	v_exp_f32_e32 v125, v125
	ds_read_b128 v[142:145], v228 offset:10240
	ds_read_b128 v[182:185], v228 offset:10752
	s_waitcnt lgkmcnt(12)
	v_mfma_f32_32x32x16_bf16 v[50:65], v[158:161], v[78:81], v[50:65]
	v_exp_f32_e32 v126, v126
	v_exp_f32_e32 v127, v127
	v_exp_f32_e32 v128, v128
	v_exp_f32_e32 v129, v129
	ds_read_b128 v[186:189], v228 offset:12288
	ds_read_b128 v[220:223], v228 offset:12800
	s_waitcnt lgkmcnt(12)
	v_mfma_f32_32x32x16_bf16 v[34:49], v[150:153], v[130:133], v[34:49]
	v_exp_f32_e32 v82, v82
	v_exp_f32_e32 v83, v83
	v_exp_f32_e32 v84, v84
	v_exp_f32_e32 v85, v85
	ds_read_b128 v[130:133], v228 offset:14336
	ds_read_b128 v[224:227], v228 offset:14848
	s_waitcnt lgkmcnt(12)
	v_mfma_f32_32x32x16_bf16 v[50:65], v[150:153], v[134:137], v[50:65]
	v_exp_f32_e32 v86, v86
	v_exp_f32_e32 v87, v87
	v_exp_f32_e32 v88, v88
	v_exp_f32_e32 v89, v89
	s_waitcnt lgkmcnt(10)
	v_mfma_f32_32x32x16_bf16 v[34:49], v[146:149], v[100:103], v[34:49]
	v_exp_f32_e32 v90, v90
	v_exp_f32_e32 v91, v91
	v_exp_f32_e32 v92, v92
	v_exp_f32_e32 v93, v93
	s_waitcnt lgkmcnt(8)
	v_mfma_f32_32x32x16_bf16 v[50:65], v[146:149], v[104:107], v[50:65]
	v_exp_f32_e32 v94, v94
	v_exp_f32_e32 v95, v95
	v_exp_f32_e32 v96, v96
	v_exp_f32_e32 v97, v97
	s_waitcnt vmcnt(0) lgkmcnt(0)
	s_barrier
	ds_read_b64_tr_b16 v[100:101], v229 offset:24576
	ds_read_b64_tr_b16 v[102:103], v229 offset:25088
	v_add_f32_e32 v66, v114, v115
	v_add_f32_e32 v66, v116, v66
	v_add_f32_e32 v66, v117, v66
	v_add_f32_e32 v66, v118, v66
	v_add_f32_e32 v99, v119, v66
	s_waitcnt lgkmcnt(9)
	v_mfma_f32_32x32x16_bf16 v[66:81], v[108:111], v[174:177], v[18:33]
	v_cvt_pk_bf16_f32 v166, v114, v115
	v_cvt_pk_bf16_f32 v167, v116, v117
	ds_read_b64_tr_b16 v[104:105], v229 offset:28672
	ds_read_b64_tr_b16 v[106:107], v229 offset:29184
	s_waitcnt lgkmcnt(10)
	v_mfma_f32_32x32x16_bf16 v[18:33], v[138:141], v[174:177], v[18:33]
	v_add_f32_e32 v99, v120, v99
	v_add_f32_e32 v99, v121, v99
	v_add_f32_e32 v99, v122, v99
	v_add_f32_e32 v99, v123, v99
	v_cvt_pk_bf16_f32 v168, v118, v119
	v_cvt_pk_bf16_f32 v169, v120, v121
	ds_read_b64_tr_b16 v[108:109], v229 offset:25600
	ds_read_b64_tr_b16 v[110:111], v229 offset:26112
	s_waitcnt lgkmcnt(11)
	v_mfma_f32_32x32x16_bf16 v[66:81], v[142:145], v[170:173], v[66:81]
	v_add_f32_e32 v99, v124, v99
	v_add_f32_e32 v99, v125, v99
	v_add_f32_e32 v99, v126, v99
	v_add_f32_e32 v99, v127, v99
	v_cvt_pk_bf16_f32 v158, v122, v123
	v_cvt_pk_bf16_f32 v159, v124, v125
	ds_read_b64_tr_b16 v[112:113], v229 offset:29696
	ds_read_b64_tr_b16 v[114:115], v229 offset:30208
	s_waitcnt lgkmcnt(12)
	v_mfma_f32_32x32x16_bf16 v[18:33], v[182:185], v[170:173], v[18:33]
	v_add_f32_e32 v99, v128, v99
	v_add_f32_e32 v99, v129, v99
	v_add_f32_e32 v99, v82, v99
	v_add_f32_e32 v99, v83, v99
	v_cvt_pk_bf16_f32 v160, v126, v127
	v_cvt_pk_bf16_f32 v161, v128, v129
	ds_read_b64_tr_b16 v[116:117], v229 offset:26624
	ds_read_b64_tr_b16 v[118:119], v229 offset:27136
	s_waitcnt lgkmcnt(13)
	v_mfma_f32_32x32x16_bf16 v[66:81], v[186:189], v[162:165], v[66:81]
	v_add_f32_e32 v99, v84, v99
	v_add_f32_e32 v99, v85, v99
	v_add_f32_e32 v99, v86, v99
	v_add_f32_e32 v99, v87, v99
	v_cvt_pk_bf16_f32 v150, v82, v83
	v_cvt_pk_bf16_f32 v151, v84, v85
	ds_read_b64_tr_b16 v[82:83], v229 offset:30720
	ds_read_b64_tr_b16 v[84:85], v229 offset:31232
	s_waitcnt lgkmcnt(14)
	v_mfma_f32_32x32x16_bf16 v[18:33], v[220:223], v[162:165], v[18:33]
	v_add_f32_e32 v99, v88, v99
	v_add_f32_e32 v99, v89, v99
	v_add_f32_e32 v99, v90, v99
	v_add_f32_e32 v99, v91, v99
	v_cvt_pk_bf16_f32 v152, v86, v87
	v_cvt_pk_bf16_f32 v153, v88, v89
	ds_read_b64_tr_b16 v[86:87], v229 offset:27648
	ds_read_b64_tr_b16 v[88:89], v229 offset:28160
	s_waitcnt lgkmcnt(14)
	v_mfma_f32_32x32x16_bf16 v[66:81], v[130:133], v[154:157], v[66:81]
	v_add_f32_e32 v99, v92, v99
	v_add_f32_e32 v99, v93, v99
	v_add_f32_e32 v99, v94, v99
	v_add_f32_e32 v99, v95, v99
	v_cvt_pk_bf16_f32 v146, v90, v91
	v_cvt_pk_bf16_f32 v147, v92, v93
	ds_read_b64_tr_b16 v[90:91], v229 offset:31744
	ds_read_b64_tr_b16 v[92:93], v229 offset:32256
	v_mfma_f32_32x32x16_bf16 v[18:33], v[224:227], v[154:157], v[18:33]
	v_add_f32_e32 v99, v96, v99
	v_add_f32_e32 v99, v97, v99
	v_add_f32_e32 v99, 0, v99
	v_cvt_pk_bf16_f32 v148, v94, v95
	v_cvt_pk_bf16_f32 v149, v96, v97
	s_mov_b32 s101, 0
	s_cmp_lt_i32 s53, s0
	s_cbranch_scc0 .Lqpf_skip
	s_add_i32 s100, s53, s1
	s_cmpk_gt_i32 s100, 0x3ff
	s_cbranch_scc1 .Lqpf_skip
	s_lshr_b32 s98, s100, 6
	s_lshl_b32 s98, s98, 11
	s_and_b32 s99, s100, 7
	s_lshl_b32 s99, s99, 8
	s_add_i32 s98, s98, s99
	s_lshl_b32 s99, s55, 5
	s_add_i32 s98, s98, s99
	s_lshl_b32 s98, s98, 10
	s_bfe_u32 s99, s100, 0x30003
	s_lshl_b32 s99, s99, 7
	s_add_i32 s98, s98, s99
	s_add_u32 s98, s33, s98
	s_addc_u32 s99, s34, 0
	global_load_dwordx4 v[174:177], v238, s[98:99] nt
	global_load_dwordx4 v[170:173], v238, s[98:99] offset:32 nt
	global_load_dwordx4 v[162:165], v238, s[98:99] offset:64 nt
	global_load_dwordx4 v[154:157], v238, s[98:99] offset:96 nt
	s_mov_b32 s101, 1
.Lqpf_skip:
	s_waitcnt lgkmcnt(14)
	v_mfma_f32_32x32x16_bf16 v[34:49], v[166:169], v[100:103], v[34:49]
	v_exp_f32_e32 v66, v66
	v_exp_f32_e32 v67, v67
	v_exp_f32_e32 v68, v68
	v_exp_f32_e32 v69, v69
	s_waitcnt lgkmcnt(12)
	v_mfma_f32_32x32x16_bf16 v[50:65], v[166:169], v[104:107], v[50:65]
	v_exp_f32_e32 v70, v70
	v_exp_f32_e32 v71, v71
	v_exp_f32_e32 v72, v72
	v_exp_f32_e32 v73, v73
	s_waitcnt lgkmcnt(10)
	v_mfma_f32_32x32x16_bf16 v[34:49], v[158:161], v[108:111], v[34:49]
	v_exp_f32_e32 v74, v74
	v_exp_f32_e32 v75, v75
	v_exp_f32_e32 v76, v76
	v_exp_f32_e32 v77, v77
	s_waitcnt lgkmcnt(8)
	v_mfma_f32_32x32x16_bf16 v[50:65], v[158:161], v[112:115], v[50:65]
	v_exp_f32_e32 v78, v78
	v_exp_f32_e32 v79, v79
	v_exp_f32_e32 v80, v80
	v_exp_f32_e32 v81, v81
	s_waitcnt lgkmcnt(6)
	v_mfma_f32_32x32x16_bf16 v[34:49], v[150:153], v[116:119], v[34:49]
	v_exp_f32_e32 v18, v18
	v_exp_f32_e32 v19, v19
	v_exp_f32_e32 v20, v20
	v_exp_f32_e32 v21, v21
	s_waitcnt lgkmcnt(4)
	v_mfma_f32_32x32x16_bf16 v[50:65], v[150:153], v[82:85], v[50:65]
	v_exp_f32_e32 v22, v22
	v_exp_f32_e32 v23, v23
	v_exp_f32_e32 v24, v24
	v_exp_f32_e32 v25, v25
	s_waitcnt lgkmcnt(2)
	v_mfma_f32_32x32x16_bf16 v[34:49], v[146:149], v[86:89], v[34:49]
	v_exp_f32_e32 v26, v26
	v_exp_f32_e32 v27, v27
	v_exp_f32_e32 v28, v28
	v_exp_f32_e32 v29, v29
	s_waitcnt lgkmcnt(0)
	v_mfma_f32_32x32x16_bf16 v[50:65], v[146:149], v[90:93], v[50:65]
	v_exp_f32_e32 v30, v30
	v_exp_f32_e32 v31, v31
	v_exp_f32_e32 v32, v32
	v_exp_f32_e32 v33, v33
	v_cvt_pk_bf16_f32 v82, v66, v67
	v_cvt_pk_bf16_f32 v83, v68, v69
	v_cvt_pk_bf16_f32 v84, v70, v71
	v_cvt_pk_bf16_f32 v85, v72, v73
	v_cvt_pk_bf16_f32 v86, v74, v75
	v_cvt_pk_bf16_f32 v87, v76, v77
	v_cvt_pk_bf16_f32 v88, v78, v79
	v_cvt_pk_bf16_f32 v89, v80, v81
	v_cvt_pk_bf16_f32 v90, v18, v19
	v_cvt_pk_bf16_f32 v91, v20, v21
	v_cvt_pk_bf16_f32 v92, v22, v23
	v_cvt_pk_bf16_f32 v93, v24, v25
	v_cvt_pk_bf16_f32 v94, v26, v27
	v_cvt_pk_bf16_f32 v95, v28, v29
	v_cvt_pk_bf16_f32 v96, v30, v31
	v_cvt_pk_bf16_f32 v97, v32, v33
	ds_read_b64_tr_b16 v[100:101],v230 offset:0
	ds_read_b64_tr_b16 v[102:103],v230 offset:512
	ds_read_b64_tr_b16 v[104:105],v230 offset:1024
	ds_read_b64_tr_b16 v[106:107],v230 offset:1536
	ds_read_b64_tr_b16 v[108:109],v230 offset:2048
	ds_read_b64_tr_b16 v[110:111],v230 offset:2560
	ds_read_b64_tr_b16 v[112:113],v230 offset:3072
	ds_read_b64_tr_b16 v[114:115],v230 offset:3584
	s_waitcnt lgkmcnt(0)
	s_nop 0
	v_mfma_f32_32x32x16_bf16 v[34:49], v[82:85], v[100:103], v[34:49]
	ds_read_b64_tr_b16 v[100:101],v230 offset:4096
	ds_read_b64_tr_b16 v[102:103],v230 offset:4608
	v_mfma_f32_32x32x16_bf16 v[34:49], v[86:89], v[104:107], v[34:49]
	ds_read_b64_tr_b16 v[104:105],v230 offset:5120
	ds_read_b64_tr_b16 v[106:107],v230 offset:5632
	v_mfma_f32_32x32x16_bf16 v[34:49], v[90:93], v[108:111], v[34:49]
	ds_read_b64_tr_b16 v[108:109],v230 offset:6144
	ds_read_b64_tr_b16 v[110:111],v230 offset:6656
	ds_read_b64_tr_b16 v[116:117],v230 offset:7168
	ds_read_b64_tr_b16 v[118:119],v230 offset:7680
	s_waitcnt lgkmcnt(0)
	v_mfma_f32_32x32x16_bf16 v[34:49], v[94:97], v[112:115], v[34:49]
	v_mfma_f32_32x32x16_bf16 v[50:65], v[82:85], v[100:103], v[50:65]
	s_waitcnt lgkmcnt(0)
	s_barrier
	s_and_b64 vcc, exec, s[26:27]
	v_mfma_f32_32x32x16_bf16 v[50:65], v[86:89], v[104:107], v[50:65]
	v_mfma_f32_32x32x16_bf16 v[50:65], v[90:93], v[108:111], v[50:65]
	v_mfma_f32_32x32x16_bf16 v[50:65], v[94:97], v[116:119], v[50:65]
	s_cbranch_vccz .LBB0_488
	s_mov_b32 s2, m0
	s_mov_b32 m0, s59
	s_nop 0
	global_load_lds_dwordx4 v[214:215], off
	s_mov_b32 m0, s2
	s_cmp_lg_u32 0, -1
	s_mov_b32 s2, m0
	s_mov_b32 m0, s58
	s_nop 0
	global_load_lds_dwordx4 v[216:217], off
	s_mov_b32 m0, s2
	s_cselect_b32 s2, 0, 0
	s_add_i32 s2, s2, s57
	s_addk_i32 s2, 0x2000
	s_mov_b32 s6, m0
	s_mov_b32 m0, s2
	s_nop 0
	global_load_lds_dwordx4 v[218:219], off
	s_mov_b32 m0, s6

	.amdhsa_kernel _Z7hyb_fwd4Args
		.amdhsa_group_segment_fixed_size 0
		.amdhsa_private_segment_fixed_size 0
		.amdhsa_kernarg_size 448
		.amdhsa_user_sgpr_count 2
		.amdhsa_user_sgpr_dispatch_ptr 0
		.amdhsa_user_sgpr_queue_ptr 0
		.amdhsa_user_sgpr_kernarg_segment_ptr 1
		.amdhsa_user_sgpr_dispatch_id 0
		.amdhsa_user_sgpr_kernarg_preload_length 0
		.amdhsa_user_sgpr_kernarg_preload_offset 0
		.amdhsa_user_sgpr_private_segment_size 0
		.amdhsa_uses_dynamic_stack 0
		.amdhsa_enable_private_segment 0
		.amdhsa_system_sgpr_workgroup_id_x 1
		.amdhsa_system_sgpr_workgroup_id_y 0
		.amdhsa_system_sgpr_workgroup_id_z 0
		.amdhsa_system_sgpr_workgroup_info 0
		.amdhsa_system_vgpr_workitem_id 0
		.amdhsa_next_free_vgpr 256
		.amdhsa_next_free_sgpr 102
		.amdhsa_accum_offset 256
		.amdhsa_reserve_vcc 1
		.amdhsa_float_round_mode_32 0
		.amdhsa_float_round_mode_16_64 0
		.amdhsa_float_denorm_mode_32 3
		.amdhsa_float_denorm_mode_16_64 3
		.amdhsa_dx10_clamp 1
		.amdhsa_ieee_mode 1
		.amdhsa_fp16_overflow 0
		.amdhsa_tg_split 0
		.amdhsa_exception_fp_ieee_invalid_op 0
		.amdhsa_exception_fp_denorm_src 0
		.amdhsa_exception_fp_ieee_div_zero 0
		.amdhsa_exception_fp_ieee_overflow 0
		.amdhsa_exception_fp_ieee_underflow 0
		.amdhsa_exception_fp_ieee_inexact 0
		.amdhsa_exception_int_div_zero 0
	.end_amdhsa_kernel

amdhsa.kernels:
  - .agpr_count:     0
    .args:
      - .offset:         0
        .size:           192
        .value_kind:     by_value
      - .offset:         192
        .size:           4
        .value_kind:     hidden_block_count_x
      - .offset:         196
        .size:           4
        .value_kind:     hidden_block_count_y
      - .offset:         200
        .size:           4
        .value_kind:     hidden_block_count_z
      - .offset:         204
        .size:           2
        .value_kind:     hidden_group_size_x
      - .offset:         206
        .size:           2
        .value_kind:     hidden_group_size_y
      - .offset:         208
        .size:           2
        .value_kind:     hidden_group_size_z
      - .offset:         210
        .size:           2
        .value_kind:     hidden_remainder_x
      - .offset:         212
        .size:           2
        .value_kind:     hidden_remainder_y
      - .offset:         214
        .size:           2
        .value_kind:     hidden_remainder_z
      - .offset:         232
        .size:           8
        .value_kind:     hidden_global_offset_x
      - .offset:         240
        .size:           8
        .value_kind:     hidden_global_offset_y
      - .offset:         248
        .size:           8
        .value_kind:     hidden_global_offset_z
      - .offset:         256
        .size:           2
        .value_kind:     hidden_grid_dims
      - .offset:         312
        .size:           4
        .value_kind:     hidden_dynamic_lds_size
    .group_segment_fixed_size: 0
    .kernarg_segment_align: 8
    .kernarg_segment_size: 448
    .language:       OpenCL C
    .language_version:
      - 2
      - 0
    .max_flat_workgroup_size: 512
    .name:           _Z7hyb_fwd4Args
    .private_segment_fixed_size: 0
    .sgpr_count:     108
    .sgpr_spill_count: 16
    .symbol:         _Z7hyb_fwd4Args.kd
    .uniform_work_group_size: 1
    .uses_dynamic_stack: false
    .vgpr_count:     256
    .vgpr_spill_count: 0
    .wavefront_size: 64
